# mixer-preparation schedule: the K/V-preparation stage of chunks 0..103 moved from the workgroups without a pass-2 tile (now pooling+scan only there) to the lightly loaded pass-2 workgroups (4 item rou
# speedup vs baseline: 1.0304x; 1.0039x over previous
.LBB0_260:
	s_add_i32 s29, s29, s42
	s_cmpk_gt_i32 s29, 0x3ff
	s_cbranch_scc1 .LBB0_323
.LBB0_261:
	s_and_b32 s4, s29, 0xff
	s_lshr_b32 s5, s29, 8
	s_and_b32 s6, s4, 31
	s_lshr_b32 s4, s4, 5
	s_cmp_ge_u32 s6, 19
	s_cbranch_scc0 .Lmp3_busy
	s_mul_i32 s4, s4, 13
	s_add_i32 s4, s4, s6
	s_sub_i32 s4, s4, 19
	s_mov_b32 s8, s4
	s_mov_b32 s10, 6
	s_cmp_eq_u32 s5, 0
	s_cbranch_scc1 .LBB0_265
	s_add_i32 s8, s4, 0x68
	s_mov_b32 s10, 4
	s_cmp_eq_u32 s5, 1
	s_cbranch_scc1 .LBB0_265
	s_cmp_eq_u32 s5, 2
	s_cbranch_scc0 .LBB0_260
	s_mov_b32 s10, 2
	s_branch .LBB0_265

.Lmp3_b2r1:
	s_cmp_eq_u32 s5, 1
	s_cbranch_scc0 .Lmp5_b2r2
	s_mov_b32 s10, 1
	s_cmp_lt_u32 s4, 32
	s_cbranch_scc0 .Lmp5_b2r1b
	s_add_i32 s8, s4, 0xb0
	s_branch .LBB0_265
.Lmp5_b2r1b:
	s_sub_i32 s8, s4, 8
	s_branch .LBB0_265
.Lmp5_b2r2:
	s_cmp_eq_u32 s5, 2
	s_cbranch_scc0 .LBB0_260
	s_cmp_lt_u32 s4, 48
	s_cbranch_scc0 .LBB0_260
	s_add_i32 s8, s4, 56
	s_mov_b32 s10, 1
	s_branch .LBB0_265
.Lmp3_b3:
	s_sub_i32 s4, s4, 0x80
	s_mov_b32 s10, 1
	s_cmp_eq_u32 s5, 3
	s_cbranch_scc0 .Lmp5_b3a
	s_mov_b32 s8, s4
	s_branch .LBB0_265
.Lmp5_b3a:
	s_mul_i32 s6, s5, 24
	s_add_i32 s8, s4, s6
	s_add_i32 s8, s8, 0x68
